# scan prologue exact t=0 override: five a2-row loads in flight with counted waits (was 64 serial load/full-wait round trips per scan item)
# baseline (speedup 1.0000x reference)
; DI float sigmoidf_(float x) { return 1.f / (1.f + __expf(-x)); }
; DI float row16_sum(float v) { v += dpp_f<0x128>(v); v += dpp_f<0x124>(v); v += dpp_f<0x122>(v); v += dpp_f<0x121>(v); return v; }
; DI void scan_item(const Params& p, int b, int h, int half, char* smem, unsigned* pgen, unsigned kp) {
;     ...
;     for (int j = 0; j < 64; ++j) {
;       const float xj = t0[16 * 64 + j];
;       const float4 a2r = *(const float4*)(p.a2 + (size_t)j * 512 + hc);
;       av[0] += xj * a2r.x; av[1] += xj * a2r.y; av[2] += xj * a2r.z; av[3] += xj * a2r.w;
;     }
;     const float4 kkw = *(const float4*)(p.k_k + hc);
;     const float4 kaw = *(const float4*)(p.k_a + hc);
;     const float4 rk = *(const float4*)(CT + 128 + lc);
;     const float kv[4] = {k0.x, k0.y, k0.z, k0.w}, kkc[4] = {kkw.x, kkw.y, kkw.z, kkw.w}, kac[4] = {kaw.x, kaw.y, kaw.z, kaw.w};
;     float kkv[4], kpv[4], aa[4], ssq = 0.f;
; #pragma unroll
;     for (int e = 0; e < 4; ++e) { aa[e] = sigmoidf_(av[e]); kkv[e] = kv[e] * kkc[e]; ssq += kkv[e] * kkv[e]; kpv[e] = kv[e] * (1.f + (aa[e] - 1.f) * kac[e]); }
;     ssq = row16_sum(ssq);
;     const float inv = rsqrtf(fmaxf(ssq, 1e-24f));
;     pr = r0;
;     pk = make_float4(kpv[0], kpv[1], kpv[2], kpv[3]);
;     pkk = make_float4(kkv[0] * inv, kkv[1] * inv, kkv[2] * inv, kkv[3] * inv);
;     pa = make_float4(aa[0], aa[1], aa[2], aa[3]);
;     pbon = row16_sum(pr.x * pk.x * rk.x + pr.y * pk.y * rk.y + pr.z * pk.z * rk.z + pr.w * pk.w * rk.w);
.LBB0_689:
	v_lshl_add_u64 v[58:59], v[134:135], 0, s[16:17]
	s_nop 3
	global_load_dwordx4 v[54:57], v1, s[18:19] offset:-12
	global_load_dwordx4 v[68:71], v1, s[18:19] offset:-28
	global_load_dwordx4 v[150:153], v[58:59], off
	global_load_dwordx4 v[154:157], v[58:59], off offset:2048
	v_add_co_u32_e32 v158, vcc, s15, v58
	s_nop 1
	v_addc_co_u32_e32 v159, vcc, 0, v59, vcc
	v_add_co_u32_e32 v212, vcc, s57, v58
	s_nop 1
	v_addc_co_u32_e32 v213, vcc, 0, v59, vcc
	v_add_co_u32_e32 v250, vcc, s66, v58
	s_nop 1
	v_addc_co_u32_e32 v251, vcc, 0, v59, vcc
	global_load_dwordx4 v[246:249], v[212:213], off offset:-4096
	global_load_dwordx4 v[200:203], v[158:159], off offset:2048
	global_load_dwordx4 v[230:233], v[212:213], off
	s_add_u32 s16, s16, 0x4000
	s_addc_u32 s17, s17, 0
	s_add_u32 s18, s18, 32
	s_addc_u32 s19, s19, 0
	s_cmp_lg_u32 s16, 0x20000
	s_waitcnt vmcnt(4)
	v_mov_b32_e32 v0, v71
	v_pk_fma_f32 v[72:73], v[68:69], v[150:151], v[50:51] op_sel_hi:[0,1,1]
	v_pk_fma_f32 v[150:151], v[68:69], v[152:153], v[52:53] op_sel_hi:[0,1,1]
	s_waitcnt vmcnt(3)
	v_pk_fma_f32 v[72:73], v[68:69], v[154:155], v[72:73] op_sel:[1,0,0]
	v_pk_fma_f32 v[68:69], v[68:69], v[156:157], v[150:151] op_sel:[1,0,0]
	global_load_dwordx4 v[154:157], v[212:213], off offset:2048
	s_waitcnt vmcnt(3)
	v_pk_fma_f32 v[72:73], v[70:71], v[246:247], v[72:73] op_sel_hi:[0,1,1]
	v_pk_fma_f32 v[68:69], v[70:71], v[248:249], v[68:69] op_sel_hi:[0,1,1]
	global_load_dwordx4 v[246:249], v[250:251], off
	s_waitcnt vmcnt(3)
	v_pk_fma_f32 v[70:71], v[0:1], v[200:201], v[72:73] op_sel_hi:[0,1,1]
	v_pk_fma_f32 v[68:69], v[0:1], v[202:203], v[68:69] op_sel_hi:[0,1,1]
	global_load_dwordx4 v[200:203], v[250:251], off offset:2048
	v_mov_b32_e32 v0, v57
	s_waitcnt vmcnt(3)
	v_pk_fma_f32 v[70:71], v[54:55], v[230:231], v[70:71] op_sel_hi:[0,1,1]
	v_pk_fma_f32 v[68:69], v[54:55], v[232:233], v[68:69] op_sel_hi:[0,1,1]
	s_waitcnt vmcnt(2)
	v_pk_fma_f32 v[70:71], v[54:55], v[154:155], v[70:71] op_sel:[1,0,0]
	v_pk_fma_f32 v[54:55], v[54:55], v[156:157], v[68:69] op_sel:[1,0,0]
	s_waitcnt vmcnt(1)
	v_pk_fma_f32 v[68:69], v[56:57], v[246:247], v[70:71] op_sel_hi:[0,1,1]
	v_pk_fma_f32 v[54:55], v[56:57], v[248:249], v[54:55] op_sel_hi:[0,1,1]
	s_waitcnt vmcnt(0)
	v_pk_fma_f32 v[50:51], v[0:1], v[200:201], v[68:69] op_sel_hi:[0,1,1]
	v_pk_fma_f32 v[52:53], v[0:1], v[202:203], v[54:55] op_sel_hi:[0,1,1]
	s_cbranch_scc1 .LBB0_689
	global_load_dwordx4 v[54:57], v[136:137], off
	v_mul_f32_e32 v0, 0xbfb8aa3b, v50
	v_exp_f32_e32 v68, v0
	v_mul_f32_e32 v0, 0xbfb8aa3b, v51
	v_exp_f32_e32 v69, v0
	v_mul_f32_e32 v0, 0xbfb8aa3b, v52
	v_exp_f32_e32 v70, v0
	v_mul_f32_e32 v0, 0xbfb8aa3b, v53
	v_exp_f32_e32 v71, v0
	s_waitcnt vmcnt(0)
	v_pk_mul_f32 v[50:51], v[46:47], v[54:55]
	s_nop 0
	v_pk_mul_f32 v[54:55], v[50:51], v[50:51]
	v_pk_mul_f32 v[52:53], v[48:49], v[56:57]
	v_add_f32_e32 v0, v54, v55
	v_pk_mul_f32 v[56:57], v[52:53], v[52:53]
	v_pk_add_f32 v[54:55], v[68:69], 1.0 op_sel_hi:[1,0]
	v_add_f32_e32 v0, v0, v56
	v_add_f32_e32 v0, v0, v57
	global_load_dwordx4 v[56:59], v[138:139], off
	s_nop 0
	v_add_f32_dpp v0, v0, v0 row_ror:8 row_mask:0xf bank_mask:0xf bound_ctrl:1
	s_nop 1
	v_add_f32_dpp v0, v0, v0 row_ror:4 row_mask:0xf bank_mask:0xf bound_ctrl:1
	s_nop 1
	v_add_f32_dpp v0, v0, v0 row_ror:2 row_mask:0xf bank_mask:0xf bound_ctrl:1
	s_nop 1
	v_add_f32_dpp v0, v0, v0 row_ror:1 row_mask:0xf bank_mask:0xf bound_ctrl:1
	v_max_f32_e32 v0, 0x179abe15, v0
	v_rsq_f32_e32 v0, v0
	s_nop 0
	v_pk_mul_f32 v[52:53], v[52:53], v[0:1] op_sel_hi:[1,0]
	v_pk_mul_f32 v[50:51], v[50:51], v[0:1] op_sel_hi:[1,0]
	v_div_scale_f32 v0, s[16:17], v55, v55, 1.0
	v_rcp_f32_e32 v68, v0
	s_nop 0
	v_fma_f32 v69, -v0, v68, 1.0
	v_fmac_f32_e32 v68, v69, v68
	v_div_scale_f32 v69, vcc, 1.0, v55, 1.0
	v_mul_f32_e32 v72, v69, v68
	v_fma_f32 v73, -v0, v72, v69
	v_fmac_f32_e32 v72, v73, v68
	v_fma_f32 v0, -v0, v72, v69
	v_div_fmas_f32 v0, v0, v68, v72
	v_div_fixup_f32 v55, v0, v55, 1.0
	v_div_scale_f32 v0, s[16:17], v54, v54, 1.0
	v_rcp_f32_e32 v68, v0
	s_nop 0
	v_fma_f32 v69, -v0, v68, 1.0
	v_fmac_f32_e32 v68, v69, v68
	v_div_scale_f32 v69, vcc, 1.0, v54, 1.0
	v_mul_f32_e32 v72, v69, v68
	v_fma_f32 v73, -v0, v72, v69
	v_fmac_f32_e32 v72, v73, v68
	v_fma_f32 v0, -v0, v72, v69
	v_div_fmas_f32 v0, v0, v68, v72
	v_div_fixup_f32 v54, v0, v54, 1.0
	v_pk_add_f32 v[68:69], v[54:55], -1.0 op_sel_hi:[1,0]
	s_waitcnt vmcnt(0)
	v_pk_fma_f32 v[56:57], v[68:69], v[56:57], 1.0 op_sel_hi:[1,1,0]
	s_nop 0
	v_pk_mul_f32 v[46:47], v[46:47], v[56:57]
	s_nop 0
	v_pk_mul_f32 v[56:57], v[38:39], v[46:47]
	s_nop 0
	v_pk_mul_f32 v[42:43], v[42:43], v[56:57]
	v_pk_add_f32 v[56:57], v[70:71], 1.0 op_sel_hi:[1,0]
	s_nop 0
	v_div_scale_f32 v0, s[16:17], v57, v57, 1.0
	v_rcp_f32_e32 v68, v0
	s_nop 0
	v_fma_f32 v69, -v0, v68, 1.0
	v_fmac_f32_e32 v68, v69, v68
	v_div_scale_f32 v69, vcc, 1.0, v57, 1.0
	v_mul_f32_e32 v70, v69, v68
	v_fma_f32 v71, -v0, v70, v69
	v_fmac_f32_e32 v70, v71, v68
	v_fma_f32 v0, -v0, v70, v69
	v_div_fmas_f32 v0, v0, v68, v70
	v_div_fixup_f32 v57, v0, v57, 1.0
	v_div_scale_f32 v0, s[16:17], v56, v56, 1.0
	v_rcp_f32_e32 v68, v0
	s_nop 0
	v_fma_f32 v69, -v0, v68, 1.0
	v_fmac_f32_e32 v68, v69, v68
	v_div_scale_f32 v69, vcc, 1.0, v56, 1.0
	v_mul_f32_e32 v70, v69, v68
	v_fma_f32 v71, -v0, v70, v69
	v_fmac_f32_e32 v70, v71, v68
	v_fma_f32 v0, -v0, v70, v69
	v_div_fmas_f32 v0, v0, v68, v70
	v_div_fixup_f32 v56, v0, v56, 1.0
	v_pk_add_f32 v[68:69], v[56:57], -1.0 op_sel_hi:[1,0]
	v_add_f32_e32 v0, v42, v43
	v_pk_fma_f32 v[58:59], v[68:69], v[58:59], 1.0 op_sel_hi:[1,1,0]
	s_nop 0
	v_pk_mul_f32 v[48:49], v[48:49], v[58:59]
	s_nop 0
	v_pk_mul_f32 v[58:59], v[40:41], v[48:49]
	s_nop 0
	v_pk_mul_f32 v[44:45], v[44:45], v[58:59]
	s_nop 0
	v_add_f32_e32 v0, v0, v44
	v_add_f32_e32 v0, v0, v45
	s_nop 1
	v_add_f32_dpp v0, v0, v0 row_ror:8 row_mask:0xf bank_mask:0xf bound_ctrl:1
	s_nop 1
	v_add_f32_dpp v0, v0, v0 row_ror:4 row_mask:0xf bank_mask:0xf bound_ctrl:1
	s_nop 1
	v_add_f32_dpp v0, v0, v0 row_ror:2 row_mask:0xf bank_mask:0xf bound_ctrl:1
	s_nop 1
	v_add_f32_dpp v0, v0, v0 row_ror:1 row_mask:0xf bank_mask:0xf bound_ctrl:1
